# LN1/LN2 row-loop stores issued as global_store instead of flat_store so the LDS-only waits do not also wait on stores
# speedup vs baseline: 1.0231x; 1.0059x over previous
; __device__ __forceinline__ void phase_ln(const float* z, float* xo, const float* __restrict__ g, const float* __restrict__ b, const float* __restrict__ sc, const float* __restrict__ sh, bf16_t* __restrict__ u) {
;     ...
;     for (int r = blockIdx.x * 8 + wave; r < S; r += 2 * stride) {
;         const bool hasB = r + stride < S; const int rr[2] = {r, hasB ? r + stride : r};
;         f32x4 v[2][8]; float s[2] = {0.f, 0.f};
; #pragma unroll
;         for (int k = 0; k < 2; ++k) { const float* zr = z + (size_t)rr[k] * DM;
; #pragma unroll
;             for (int j = 0; j < 8; ++j) v[k][j] = *(const f32x4*)(zr + j * 256 + 4 * lane); }
; #pragma unroll
;         for (int k = 0; k < 2; ++k)
; #pragma unroll
;             for (int j = 0; j < 8; ++j) s[k] += (v[k][j][0] + v[k][j][1]) + (v[k][j][2] + v[k][j][3]);
;         float mean[2], rstd[2];
; #pragma unroll
;         for (int k = 0; k < 2; ++k) { mean[k] = wave_sum(s[k]) * (1.0f / DM); float q = 0.f;
; #pragma unroll
;             for (int j = 0; j < 8; ++j) { const f32x4 d = v[k][j] - mean[k]; q += (d[0] * d[0] + d[1] * d[1]) + (d[2] * d[2] + d[3] * d[3]); }
.LBB0_1073:
	v_lshl_add_u64 v[172:173], s[2:3], 0, v[168:169]
	v_add_co_u32_e32 v182, vcc, 0xb828000, v172
	v_add_u32_e32 v0, s16, v80
	s_nop 0
	v_addc_co_u32_e32 v183, vcc, 0, v173, vcc
	flat_load_dwordx4 v[74:77], v[182:183]
	flat_load_dwordx4 v[66:69], v[182:183] offset:1024
	flat_load_dwordx4 v[58:61], v[182:183] offset:2048
	flat_load_dwordx4 v[50:53], v[182:183] offset:3072
	v_add_co_u32_e32 v14, vcc, 0xb829000, v172
	v_cmp_gt_i32_e64 s[4:5], s17, v0
	s_nop 0
	v_addc_co_u32_e32 v15, vcc, 0, v173, vcc
	flat_load_dwordx4 v[42:45], v[14:15]
	flat_load_dwordx4 v[34:37], v[14:15] offset:1024
	flat_load_dwordx4 v[26:29], v[14:15] offset:2048
	flat_load_dwordx4 v[18:21], v[14:15] offset:3072
	v_cndmask_b32_e64 v78, v80, v0, s[4:5]
	v_ashrrev_i32_e32 v79, 31, v78
	v_lshlrev_b64 v[170:171], 13, v[78:79]
	v_lshl_add_u64 v[198:199], v[126:127], 0, v[170:171]
	flat_load_dwordx4 v[70:73], v[198:199]
	flat_load_dwordx4 v[62:65], v[198:199] offset:1024
	flat_load_dwordx4 v[54:57], v[198:199] offset:2048
	flat_load_dwordx4 v[46:49], v[198:199] offset:3072
	v_add_co_u32_e32 v14, vcc, s18, v198
	v_lshl_add_u64 v[184:185], s[2:3], 0, v[166:167]
	s_nop 0
	v_addc_co_u32_e32 v15, vcc, 0, v199, vcc
	flat_load_dwordx4 v[38:41], v[14:15]
	flat_load_dwordx4 v[30:33], v[14:15] offset:1024
	flat_load_dwordx4 v[22:25], v[14:15] offset:2048
	s_nop 0
	flat_load_dwordx4 v[14:17], v[14:15] offset:3072
	s_waitcnt vmcnt(0) lgkmcnt(0)
	v_add_f32_e32 v0, v74, v75
	v_add_f32_e32 v81, v76, v77
	v_add_f32_e32 v0, v0, v81
	v_add_f32_e32 v81, v66, v67
	v_add_f32_e32 v174, v68, v69
	v_add_f32_e32 v0, 0, v0
	v_add_f32_e32 v81, v81, v174
	v_add_f32_e32 v0, v0, v81
	v_add_f32_e32 v81, v58, v59
	v_add_f32_e32 v174, v60, v61
	v_add_f32_e32 v81, v81, v174
	v_add_f32_e32 v0, v0, v81
	v_add_f32_e32 v81, v50, v51
	v_add_f32_e32 v174, v52, v53
	v_add_f32_e32 v81, v81, v174
	v_add_f32_e32 v0, v0, v81
	v_add_f32_e32 v81, v42, v43
	v_add_f32_e32 v174, v44, v45
	v_add_f32_e32 v81, v81, v174
	v_add_f32_e32 v0, v0, v81
	v_add_f32_e32 v81, v34, v35
	v_add_f32_e32 v174, v36, v37
	v_add_f32_e32 v81, v81, v174
	v_add_f32_e32 v0, v0, v81
	v_add_f32_e32 v81, v26, v27
	v_add_f32_e32 v174, v28, v29
	v_add_f32_e32 v81, v81, v174
	v_add_f32_e32 v0, v0, v81
	v_add_f32_e32 v81, v18, v19
	v_add_f32_e32 v174, v20, v21
	v_add_f32_e32 v81, v81, v174
	v_add_f32_e32 v0, v0, v81
	v_add_f32_e32 v81, v70, v71
	v_add_f32_e32 v174, v72, v73
	v_add_f32_e32 v81, v81, v174
	v_add_f32_e32 v174, v62, v63
	v_add_f32_e32 v175, v64, v65
	v_add_f32_e32 v81, 0, v81
	v_add_f32_e32 v174, v174, v175
	v_add_f32_e32 v81, v81, v174
	v_add_f32_e32 v174, v54, v55
	v_add_f32_e32 v175, v56, v57
	v_add_f32_e32 v174, v174, v175
	v_add_f32_e32 v81, v81, v174
	v_add_f32_e32 v174, v46, v47
	v_add_f32_e32 v175, v48, v49
	v_add_f32_e32 v174, v174, v175
	v_add_f32_e32 v81, v81, v174
	v_add_f32_e32 v174, v38, v39
	v_add_f32_e32 v175, v40, v41
	v_add_f32_e32 v174, v174, v175
	v_add_f32_e32 v81, v81, v174
	v_add_f32_e32 v174, v30, v31
	v_add_f32_e32 v175, v32, v33
	v_add_f32_e32 v174, v174, v175
	v_add_f32_e32 v81, v81, v174
	v_add_f32_e32 v174, v22, v23
	v_add_f32_e32 v175, v24, v25
	v_add_f32_dpp v0, v0, v0 quad_perm:[1,0,3,2] row_mask:0xf bank_mask:0xf bound_ctrl:1
	v_add_f32_e32 v174, v174, v175
	v_add_f32_e32 v81, v81, v174
	v_add_f32_dpp v0, v0, v0 quad_perm:[2,3,0,1] row_mask:0xf bank_mask:0xf bound_ctrl:1
	v_add_f32_e32 v174, v14, v15
	v_add_f32_e32 v175, v16, v17
	v_add_f32_dpp v0, v0, v0 row_half_mirror row_mask:0xf bank_mask:0xf bound_ctrl:1
	v_add_f32_e32 v174, v174, v175
	v_add_f32_e32 v81, v81, v174
	v_add_f32_dpp v0, v0, v0 row_mirror row_mask:0xf bank_mask:0xf bound_ctrl:1
	v_mov_b32_e32 v174, v0
	s_nop 1
	v_permlane16_swap_b32_e32 v0, v174
	v_add_f32_e32 v0, v0, v174
	v_mov_b32_e32 v174, v0
	s_nop 1
	v_permlane32_swap_b32_e32 v0, v174
	v_add_f32_e32 v0, v0, v174
	v_mov_b32_e32 v240, v0
	v_fmamk_f32 v77, v0, 0xba000000, v77
	v_fmac_f32_e32 v75, 0xba000000, v0
	v_fmamk_f32 v203, v0, 0xba000000, v69
	v_fmamk_f32 v67, v0, 0xba000000, v67
	v_fmamk_f32 v76, v0, 0xba000000, v76
	v_fmamk_f32 v74, v0, 0xba000000, v74
	v_mul_f32_e32 v174, v75, v75
	v_mul_f32_e32 v175, v77, v77
	v_fmamk_f32 v202, v0, 0xba000000, v68
	v_fmac_f32_e32 v66, 0xba000000, v0
	v_mul_f32_e32 v68, v67, v67
	v_mul_f32_e32 v69, v203, v203
	v_fmamk_f32 v201, v0, 0xba000000, v61
	v_fmamk_f32 v59, v0, 0xba000000, v59
	v_fmac_f32_e32 v174, v74, v74
	v_fmac_f32_e32 v175, v76, v76
	v_fmac_f32_e32 v68, v66, v66
	v_fmac_f32_e32 v69, v202, v202
	v_fmamk_f32 v200, v0, 0xba000000, v60
	v_fmac_f32_e32 v58, 0xba000000, v0
	v_mul_f32_e32 v60, v59, v59
	v_mul_f32_e32 v61, v201, v201
	v_fmamk_f32 v197, v0, 0xba000000, v53
	v_fmamk_f32 v51, v0, 0xba000000, v51
	v_add_f32_e32 v174, v174, v175
	v_add_f32_e32 v68, v68, v69
	v_fmac_f32_e32 v60, v58, v58
	v_fmac_f32_e32 v61, v200, v200
	v_fmamk_f32 v196, v0, 0xba000000, v52
	v_fmac_f32_e32 v50, 0xba000000, v0
	v_mul_f32_e32 v52, v51, v51
	v_mul_f32_e32 v53, v197, v197
	v_fmamk_f32 v195, v0, 0xba000000, v45
	v_fmamk_f32 v43, v0, 0xba000000, v43
	v_add_f32_e32 v68, v174, v68
	v_add_f32_e32 v60, v60, v61
	v_fmac_f32_e32 v52, v50, v50
	v_fmac_f32_e32 v53, v196, v196
	v_fmamk_f32 v194, v0, 0xba000000, v44
	v_fmac_f32_e32 v42, 0xba000000, v0
	v_mul_f32_e32 v44, v43, v43
	v_mul_f32_e32 v45, v195, v195
	v_fmamk_f32 v181, v0, 0xba000000, v37
	v_fmamk_f32 v35, v0, 0xba000000, v35
	v_add_f32_e32 v60, v60, v68
	v_add_f32_e32 v52, v52, v53
	v_fmac_f32_e32 v44, v42, v42
	v_fmac_f32_e32 v45, v194, v194
	v_fmamk_f32 v180, v0, 0xba000000, v36
	v_fmac_f32_e32 v34, 0xba000000, v0
	v_mul_f32_e32 v36, v35, v35
	v_mul_f32_e32 v37, v181, v181
; __device__ __forceinline__ void phase_ln(const float* z, float* xo, const float* __restrict__ g, const float* __restrict__ b, const float* __restrict__ sc, const float* __restrict__ sh, bf16_t* __restrict__ u) {
;     ...
;         for (int k = 0; k < 2; ++k) { mean[k] = wave_sum(s[k]) * (1.0f / DM); float q = 0.f;
; #pragma unroll
;             for (int j = 0; j < 8; ++j) { const f32x4 d = v[k][j] - mean[k]; q += (d[0] * d[0] + d[1] * d[1]) + (d[2] * d[2] + d[3] * d[3]); }
;             rstd[k] = 1.0f / sqrtf(wave_sum(q) * (1.0f / DM) + 1e-5f); }
	v_fmamk_f32 v179, v0, 0xba000000, v29
	v_fmamk_f32 v27, v0, 0xba000000, v27
	v_add_f32_e32 v52, v52, v60
	v_add_f32_e32 v44, v44, v45
	v_fmac_f32_e32 v36, v34, v34
	v_fmac_f32_e32 v37, v180, v180
	v_fmamk_f32 v178, v0, 0xba000000, v28
	v_fmac_f32_e32 v26, 0xba000000, v0
	v_mul_f32_e32 v28, v27, v27
	v_mul_f32_e32 v29, v179, v179
	v_fmamk_f32 v175, v0, 0xba000000, v21
	v_fmamk_f32 v19, v0, 0xba000000, v19
	v_add_f32_e32 v44, v44, v52
	v_add_f32_e32 v36, v36, v37
	v_fmac_f32_e32 v28, v26, v26
	v_fmac_f32_e32 v29, v178, v178
	v_fmamk_f32 v174, v0, 0xba000000, v20
	v_fmac_f32_e32 v18, 0xba000000, v0
	v_mul_f32_e32 v0, v19, v19
	v_mul_f32_e32 v20, v175, v175
	v_add_f32_e32 v36, v36, v44
	v_add_f32_e32 v28, v28, v29
	v_fmac_f32_e32 v0, v18, v18
	v_fmac_f32_e32 v20, v174, v174
	v_add_f32_e32 v28, v28, v36
	v_add_f32_e32 v0, v0, v20
	v_add_f32_e32 v0, v0, v28
	s_nop 1
	v_add_f32_dpp v0, v0, v0 quad_perm:[1,0,3,2] row_mask:0xf bank_mask:0xf bound_ctrl:1
	s_nop 1
	v_add_f32_dpp v0, v0, v0 quad_perm:[2,3,0,1] row_mask:0xf bank_mask:0xf bound_ctrl:1
	s_nop 1
	v_add_f32_dpp v0, v0, v0 row_half_mirror row_mask:0xf bank_mask:0xf bound_ctrl:1
	s_nop 1
	v_add_f32_dpp v0, v0, v0 row_mirror row_mask:0xf bank_mask:0xf bound_ctrl:1
	v_mov_b32_e32 v20, v0
	s_nop 1
	v_permlane16_swap_b32_e32 v0, v20
	v_add_f32_e32 v0, v0, v20
	v_mov_b32_e32 v20, v0
	s_nop 1
	v_permlane32_swap_b32_e32 v0, v20
	v_add_f32_e32 v0, v0, v20
	v_fmamk_f32 v0, v0, 0x3a000000, v220
	v_cmp_gt_f32_e32 vcc, s77, v0
	v_mul_f32_e32 v20, 0x4f800000, v0
	s_nop 0
	v_cndmask_b32_e32 v0, v0, v20, vcc
	v_sqrt_f32_e32 v20, v0
	s_nop 0
	v_add_u32_e32 v21, -1, v20
	v_fma_f32 v28, -v21, v20, v0
	v_cmp_ge_f32_e64 s[0:1], 0, v28
	v_add_u32_e32 v28, 1, v20
	s_nop 0
	v_cndmask_b32_e64 v21, v20, v21, s[0:1]
	v_fma_f32 v20, -v28, v20, v0
	v_cmp_lt_f32_e64 s[0:1], 0, v20
	s_nop 1
	v_cndmask_b32_e64 v20, v21, v28, s[0:1]
	v_mul_f32_e32 v21, 0x37800000, v20
	v_cndmask_b32_e32 v20, v20, v21, vcc
	v_cmp_class_f32_e32 vcc, v0, v219
	s_nop 1
	v_cndmask_b32_e32 v0, v20, v0, vcc
	v_div_scale_f32 v20, s[0:1], v0, v0, 1.0
	v_rcp_f32_e32 v21, v20
	s_nop 0
	v_fma_f32 v28, -v20, v21, 1.0
	v_fmac_f32_e32 v21, v28, v21
	v_div_scale_f32 v28, vcc, 1.0, v0, 1.0
	v_mul_f32_e32 v29, v28, v21
	v_fma_f32 v36, -v20, v29, v28
	v_fmac_f32_e32 v29, v36, v21
	v_fma_f32 v20, -v20, v29, v28
	v_div_fmas_f32 v20, v20, v21, v29
	v_div_fixup_f32 v176, v20, v0, 1.0
	v_add_f32_dpp v0, v81, v81 quad_perm:[1,0,3,2] row_mask:0xf bank_mask:0xf bound_ctrl:1
	s_nop 1
	v_add_f32_dpp v0, v0, v0 quad_perm:[2,3,0,1] row_mask:0xf bank_mask:0xf bound_ctrl:1
	s_nop 1
	v_add_f32_dpp v0, v0, v0 row_half_mirror row_mask:0xf bank_mask:0xf bound_ctrl:1
	s_nop 1
	v_add_f32_dpp v0, v0, v0 row_mirror row_mask:0xf bank_mask:0xf bound_ctrl:1
	v_mov_b32_e32 v20, v0
	s_nop 1
	v_permlane16_swap_b32_e32 v0, v20
	v_add_f32_e32 v0, v0, v20
	v_mov_b32_e32 v20, v0
	s_nop 1
	v_permlane32_swap_b32_e32 v0, v20
	v_add_f32_e32 v0, v0, v20
	v_mov_b32_e32 v241, v0
	v_fmamk_f32 v69, v0, 0xba000000, v73
	v_fmamk_f32 v71, v0, 0xba000000, v71
	v_fmamk_f32 v68, v0, 0xba000000, v72
	v_fmac_f32_e32 v70, 0xba000000, v0
	v_mul_f32_e32 v20, v71, v71
	v_mul_f32_e32 v21, v69, v69
	v_fmac_f32_e32 v20, v70, v70
	v_fmac_f32_e32 v21, v68, v68
	v_fmamk_f32 v61, v0, 0xba000000, v65
	v_fmamk_f32 v63, v0, 0xba000000, v63
	v_add_f32_e32 v20, v20, v21
	v_fmamk_f32 v60, v0, 0xba000000, v64
	v_fmac_f32_e32 v62, 0xba000000, v0
	v_mul_f32_e32 v21, v63, v63
	v_mul_f32_e32 v28, v61, v61
	v_fmac_f32_e32 v21, v62, v62
	v_fmac_f32_e32 v28, v60, v60
	v_add_f32_e32 v21, v21, v28
	v_fmamk_f32 v53, v0, 0xba000000, v57
	v_fmamk_f32 v55, v0, 0xba000000, v55
	v_add_f32_e32 v20, v20, v21
	v_fmamk_f32 v52, v0, 0xba000000, v56
	v_fmac_f32_e32 v54, 0xba000000, v0
	v_mul_f32_e32 v21, v55, v55
	v_mul_f32_e32 v28, v53, v53
	v_fmac_f32_e32 v21, v54, v54
	v_fmac_f32_e32 v28, v52, v52
	v_add_f32_e32 v21, v21, v28
	v_fmamk_f32 v45, v0, 0xba000000, v49
	v_fmamk_f32 v47, v0, 0xba000000, v47
	v_add_f32_e32 v20, v21, v20
	v_fmamk_f32 v44, v0, 0xba000000, v48
	v_fmac_f32_e32 v46, 0xba000000, v0
	v_mul_f32_e32 v21, v47, v47
	v_mul_f32_e32 v28, v45, v45
	v_fmac_f32_e32 v21, v46, v46
	v_fmac_f32_e32 v28, v44, v44
	v_add_f32_e32 v21, v21, v28
	v_fmamk_f32 v37, v0, 0xba000000, v41
	v_fmamk_f32 v39, v0, 0xba000000, v39
	v_add_f32_e32 v20, v21, v20
	v_fmamk_f32 v36, v0, 0xba000000, v40
	v_fmac_f32_e32 v38, 0xba000000, v0
	v_mul_f32_e32 v21, v39, v39
	v_mul_f32_e32 v28, v37, v37
	v_fmac_f32_e32 v21, v38, v38
	v_fmac_f32_e32 v28, v36, v36
	v_add_f32_e32 v21, v21, v28
	v_fmamk_f32 v29, v0, 0xba000000, v33
	v_fmamk_f32 v31, v0, 0xba000000, v31
	v_add_f32_e32 v20, v21, v20
	v_fmamk_f32 v28, v0, 0xba000000, v32
	v_fmac_f32_e32 v30, 0xba000000, v0
	v_mul_f32_e32 v21, v31, v31
	v_mul_f32_e32 v32, v29, v29
	v_fmac_f32_e32 v21, v30, v30
	v_fmac_f32_e32 v32, v28, v28
	v_add_f32_e32 v21, v21, v32
	v_add_f32_e32 v32, v21, v20
	v_fmamk_f32 v21, v0, 0xba000000, v25
	v_fmamk_f32 v23, v0, 0xba000000, v23
	v_fmamk_f32 v20, v0, 0xba000000, v24
	v_fmac_f32_e32 v22, 0xba000000, v0
	v_mul_f32_e32 v24, v23, v23
	v_mul_f32_e32 v25, v21, v21
	v_fmac_f32_e32 v24, v22, v22
	v_fmac_f32_e32 v25, v20, v20
	v_fmamk_f32 v17, v0, 0xba000000, v17
	v_fmamk_f32 v15, v0, 0xba000000, v15
	v_add_f32_e32 v24, v24, v25
	v_fmamk_f32 v16, v0, 0xba000000, v16
	v_fmac_f32_e32 v14, 0xba000000, v0
	v_mul_f32_e32 v0, v15, v15
	v_mul_f32_e32 v25, v17, v17
	v_fmac_f32_e32 v0, v14, v14
	v_fmac_f32_e32 v25, v16, v16
	v_add_f32_e32 v24, v24, v32
	v_add_f32_e32 v0, v0, v25
	v_add_f32_e32 v0, v0, v24
	s_nop 1
	v_add_f32_dpp v0, v0, v0 quad_perm:[1,0,3,2] row_mask:0xf bank_mask:0xf bound_ctrl:1
; __device__ __forceinline__ unsigned cvt_pk_bf16(float lo, float hi) { unsigned r; asm volatile("v_cvt_pk_bf16_f32 %0, %1, %2" : "=v"(r) : "v"(lo), "v"(hi)); return r; }
; template <int CTRL> __device__ __forceinline__ float dpp_mov(float v) { return __builtin_bit_cast(float, __builtin_amdgcn_update_dpp(0, __builtin_bit_cast(int, v), CTRL, 0xf, 0xf, true)); }
; __device__ __forceinline__ float wave_sum(float v) {
;     v += dpp_mov<0xB1>(v);
;     v += dpp_mov<0x4E>(v);
;     v += dpp_mov<0x141>(v);
;     v += dpp_mov<0x140>(v);
;     { auto rr = __builtin_amdgcn_permlane16_swap(__float_as_uint(v), __float_as_uint(v), false, false); v = __uint_as_float(rr[0]) + __uint_as_float(rr[1]); }
;     { auto rr = __builtin_amdgcn_permlane32_swap(__float_as_uint(v), __float_as_uint(v), false, false); v = __uint_as_float(rr[0]) + __uint_as_float(rr[1]); }
; __device__ __forceinline__ void phase_ln(const float* z, float* xo, const float* __restrict__ g, const float* __restrict__ b, const float* __restrict__ sc, const float* __restrict__ sh, bf16_t* __restrict__ u) {
;     ...
;         for (int k = 0; k < 2; ++k) { mean[k] = wave_sum(s[k]) * (1.0f / DM); float q = 0.f;
; #pragma unroll
;             for (int j = 0; j < 8; ++j) { const f32x4 d = v[k][j] - mean[k]; q += (d[0] * d[0] + d[1] * d[1]) + (d[2] * d[2] + d[3] * d[3]); }
;             rstd[k] = 1.0f / sqrtf(wave_sum(q) * (1.0f / DM) + 1e-5f); }
; #pragma unroll
;         for (int j = 0; j < 8; ++j) { const int col = j * 256 + 4 * lane;
;             const f32x4 gg = *(const f32x4*)(g + col), bb = *(const f32x4*)(b + col);
;             f32x4 s1 = {0.f, 0.f, 0.f, 0.f}, h1 = {0.f, 0.f, 0.f, 0.f};
;             if (u) { s1 = *(const f32x4*)(sc + col) + 1.0f; h1 = *(const f32x4*)(sh + col); }
; #pragma unroll
;             for (int k = 0; k < 2; ++k) { if (k == 1 && !hasB) continue;
;                 const f32x4 o = (v[k][j] - mean[k]) * rstd[k] * gg + bb;
;                 *(f32x4*)(xo + (size_t)rr[k] * DM + col) = o;
;                 if (u) { const f32x4 m = o * s1 + h1; u32x2 w; w.x = cvt_pk_bf16(m[0], m[1]); w.y = cvt_pk_bf16(m[2], m[3]); *(u32x2*)(u + (size_t)rr[k] * DM + col) = w; } } }
	s_nop 1
	v_add_f32_dpp v0, v0, v0 quad_perm:[2,3,0,1] row_mask:0xf bank_mask:0xf bound_ctrl:1
	s_nop 1
	v_add_f32_dpp v0, v0, v0 row_half_mirror row_mask:0xf bank_mask:0xf bound_ctrl:1
	s_nop 1
	v_add_f32_dpp v0, v0, v0 row_mirror row_mask:0xf bank_mask:0xf bound_ctrl:1
	v_mov_b32_e32 v24, v0
	s_nop 1
	v_permlane16_swap_b32_e32 v0, v24
	v_add_f32_e32 v0, v0, v24
	v_mov_b32_e32 v24, v0
	s_nop 1
	v_permlane32_swap_b32_e32 v0, v24
	v_add_f32_e32 v0, v0, v24
	v_fmamk_f32 v0, v0, 0x3a000000, v220
	v_cmp_gt_f32_e32 vcc, s77, v0
	v_mul_f32_e32 v24, 0x4f800000, v0
	s_nop 0
	v_cndmask_b32_e32 v0, v0, v24, vcc
	v_sqrt_f32_e32 v24, v0
	s_nop 0
	v_add_u32_e32 v25, -1, v24
	v_fma_f32 v32, -v25, v24, v0
	v_cmp_ge_f32_e64 s[0:1], 0, v32
	v_add_u32_e32 v32, 1, v24
	s_nop 0
	v_cndmask_b32_e64 v25, v24, v25, s[0:1]
	v_fma_f32 v24, -v32, v24, v0
	v_cmp_lt_f32_e64 s[0:1], 0, v24
	s_nop 1
	v_cndmask_b32_e64 v24, v25, v32, s[0:1]
	v_mul_f32_e32 v25, 0x37800000, v24
	v_cndmask_b32_e32 v24, v24, v25, vcc
	v_cmp_class_f32_e32 vcc, v0, v219
	s_nop 1
	v_cndmask_b32_e32 v0, v24, v0, vcc
	v_div_scale_f32 v24, s[0:1], v0, v0, 1.0
	v_rcp_f32_e32 v25, v24
	s_nop 0
	v_fma_f32 v32, -v24, v25, 1.0
	v_fmac_f32_e32 v25, v32, v25
	v_div_scale_f32 v32, vcc, 1.0, v0, 1.0
	v_mul_f32_e32 v33, v32, v25
	v_fma_f32 v40, -v24, v33, v32
	v_fmac_f32_e32 v33, v40, v25
	v_fma_f32 v24, -v24, v33, v32
	v_div_fmas_f32 v24, v24, v25, v33
	v_div_fixup_f32 v0, v24, v0, 1.0
	s_add_u32 s0, s2, 0xb818000
	s_addc_u32 s1, s3, 0
	v_lshlrev_b32_e32 v242, 3, v80
	v_lshlrev_b32_e32 v243, 3, v78
	v_mov_b32_e32 v244, v240
	v_mov_b32_e32 v245, v176
	v_mov_b32_e32 v246, v241
	v_mov_b32_e32 v247, v0
	global_store_dwordx2 v242, v[244:245], s[0:1]
	global_store_dwordx2 v243, v[246:247], s[0:1]
	v_pk_mul_f32 v[24:25], v[74:75], v[176:177] op_sel_hi:[1,0]
	v_pk_mul_f32 v[32:33], v[76:77], v[176:177] op_sel_hi:[1,0]
	v_pk_fma_f32 v[72:73], v[10:11], v[24:25], v[2:3]
	v_pk_fma_f32 v[74:75], v[12:13], v[32:33], v[4:5]
	v_pk_fma_f32 v[32:33], v[72:73], v[156:157], v[6:7]
	v_pk_fma_f32 v[24:25], v[74:75], v[154:155], v[8:9]
	v_cvt_pk_bf16_f32 v32, v32, v33
	v_cvt_pk_bf16_f32 v33, v24, v25
	v_add_co_u32_e32 v24, vcc, 0xf828000, v184
	v_lshlrev_b64 v[182:183], 12, v[78:79]
	s_nop 0
	v_addc_co_u32_e32 v25, vcc, 0, v185, vcc
	global_store_dwordx2 v[24:25], v[32:33], off
	s_and_saveexec_b64 s[0:1], s[4:5]
	s_cbranch_execz .LBB0_1075
	v_pk_mul_f32 v[24:25], v[68:69], v[0:1] op_sel_hi:[1,0]
	v_pk_mul_f32 v[32:33], v[70:71], v[0:1] op_sel_hi:[1,0]
	v_pk_fma_f32 v[70:71], v[12:13], v[24:25], v[4:5]
	v_pk_fma_f32 v[68:69], v[10:11], v[32:33], v[2:3]
	v_pk_fma_f32 v[24:25], v[154:155], v[70:71], v[8:9]
	v_pk_fma_f32 v[32:33], v[156:157], v[68:69], v[6:7]
	v_cvt_pk_bf16_f32 v32, v32, v33
	v_cvt_pk_bf16_f32 v33, v24, v25
	v_lshl_add_u64 v[24:25], v[140:141], 0, v[182:183]
	global_store_dwordx2 v[24:25], v[32:33], off
.LBB0_1075:
	s_or_b64 exec, exec, s[0:1]
	ds_read_b128 v[68:71], v252 offset:1024
	ds_read_b128 v[72:75], v252 offset:9216
	ds_read_b128 v[76:79], v252 offset:17408
	v_mov_b32_e32 v177, v176
	v_mov_b32_e32 v24, v176
	v_mov_b32_e32 v25, v176
	s_mov_b64 s[0:1], 0xb828400
	v_pk_mul_f32 v[56:57], v[202:203], v[24:25]
	v_pk_mul_f32 v[64:65], v[66:67], v[176:177]
	v_lshl_add_u64 v[48:49], v[172:173], 0, s[0:1]
	s_waitcnt lgkmcnt(0)
	v_pk_fma_f32 v[66:67], v[56:57], v[70:71], v[74:75]
	v_pk_add_f32 v[32:33], v[78:79], 1.0 op_sel_hi:[1,0]
	v_pk_add_f32 v[40:41], v[76:77], 1.0 op_sel_hi:[1,0]
	ds_read_b128 v[76:79], v252 offset:25600
	v_pk_fma_f32 v[64:65], v[64:65], v[68:69], v[72:73]
	s_waitcnt lgkmcnt(0)
	v_pk_fma_f32 v[48:49], v[66:67], v[32:33], v[78:79]
	v_pk_fma_f32 v[56:57], v[64:65], v[40:41], v[76:77]
	s_nop 0
	v_cvt_pk_bf16_f32 v56, v56, v57
	v_cvt_pk_bf16_f32 v57, v48, v49
	v_add_co_u32_e32 v48, vcc, 0xf828000, v184
	s_nop 1
	v_addc_co_u32_e32 v49, vcc, 0, v185, vcc
	global_store_dwordx2 v[48:49], v[56:57], off offset:512
	s_and_saveexec_b64 s[0:1], s[4:5]
	s_cbranch_execz .LBB0_1077
	v_pk_mul_f32 v[48:49], v[60:61], v[0:1] op_sel_hi:[1,0]
	v_pk_mul_f32 v[56:57], v[62:63], v[0:1] op_sel_hi:[1,0]
	v_pk_fma_f32 v[62:63], v[48:49], v[70:71], v[74:75]
	v_pk_fma_f32 v[60:61], v[56:57], v[68:69], v[72:73]
	v_lshl_add_u64 v[48:49], v[146:147], 0, v[170:171]
	v_pk_fma_f32 v[32:33], v[62:63], v[32:33], v[78:79]
	v_pk_fma_f32 v[40:41], v[60:61], v[40:41], v[76:77]
	v_cvt_pk_bf16_f32 v40, v40, v41
	v_cvt_pk_bf16_f32 v41, v32, v33
	v_lshl_add_u64 v[32:33], v[148:149], 0, v[182:183]
	global_store_dwordx2 v[32:33], v[40:41], off
.LBB0_1077:
	s_or_b64 exec, exec, s[0:1]
	ds_read_b128 v[72:75], v252 offset:18432
	ds_read_b128 v[64:67], v252 offset:2048
	ds_read_b128 v[68:71], v252 offset:10240
	ds_read_b128 v[60:63], v252 offset:26624
	v_pk_mul_f32 v[48:49], v[58:59], v[176:177]
	s_mov_b64 s[0:1], 0xb828800
	v_pk_mul_f32 v[40:41], v[200:201], v[24:25]
	v_add_co_u32_e32 v76, vcc, 0xf828000, v184
	v_lshl_add_u64 v[78:79], v[172:173], 0, s[0:1]
	s_nop 0
	v_addc_co_u32_e32 v77, vcc, 0, v185, vcc
	s_waitcnt lgkmcnt(0)
	v_pk_add_f32 v[32:33], v[72:73], 1.0 op_sel_hi:[1,0]
	v_pk_add_f32 v[24:25], v[74:75], 1.0 op_sel_hi:[1,0]
	v_pk_fma_f32 v[56:57], v[48:49], v[64:65], v[68:69]
	v_pk_fma_f32 v[58:59], v[40:41], v[66:67], v[70:71]
	v_pk_fma_f32 v[48:49], v[56:57], v[32:33], v[60:61]
	v_pk_fma_f32 v[40:41], v[58:59], v[24:25], v[62:63]
	v_cvt_pk_bf16_f32 v48, v48, v49
	s_nop 0
	v_cvt_pk_bf16_f32 v49, v40, v41
	global_store_dwordx2 v[76:77], v[48:49], off offset:1024
	s_and_saveexec_b64 s[0:1], s[4:5]
	s_cbranch_execz .LBB0_1079
	v_pk_mul_f32 v[40:41], v[52:53], v[0:1] op_sel_hi:[1,0]
	v_pk_mul_f32 v[48:49], v[54:55], v[0:1] op_sel_hi:[1,0]
	v_pk_fma_f32 v[54:55], v[40:41], v[66:67], v[70:71]
	v_pk_fma_f32 v[52:53], v[48:49], v[64:65], v[68:69]
	v_lshl_add_u64 v[40:41], v[136:137], 0, v[170:171]
	v_pk_fma_f32 v[24:25], v[54:55], v[24:25], v[62:63]
	v_pk_fma_f32 v[32:33], v[52:53], v[32:33], v[60:61]
	v_cvt_pk_bf16_f32 v32, v32, v33
	v_cvt_pk_bf16_f32 v33, v24, v25
	v_lshl_add_u64 v[24:25], v[150:151], 0, v[182:183]
	global_store_dwordx2 v[24:25], v[32:33], off
; __device__ __forceinline__ unsigned cvt_pk_bf16(float lo, float hi) { unsigned r; asm volatile("v_cvt_pk_bf16_f32 %0, %1, %2" : "=v"(r) : "v"(lo), "v"(hi)); return r; }
; __device__ __forceinline__ void phase_ln(const float* z, float* xo, const float* __restrict__ g, const float* __restrict__ b, const float* __restrict__ sc, const float* __restrict__ sh, bf16_t* __restrict__ u) {
;     ...
;         for (int j = 0; j < 8; ++j) { const int col = j * 256 + 4 * lane;
;             const f32x4 gg = *(const f32x4*)(g + col), bb = *(const f32x4*)(b + col);
;             f32x4 s1 = {0.f, 0.f, 0.f, 0.f}, h1 = {0.f, 0.f, 0.f, 0.f};
;             if (u) { s1 = *(const f32x4*)(sc + col) + 1.0f; h1 = *(const f32x4*)(sh + col); }
; #pragma unroll
;             for (int k = 0; k < 2; ++k) { if (k == 1 && !hasB) continue;
;                 const f32x4 o = (v[k][j] - mean[k]) * rstd[k] * gg + bb;
;                 *(f32x4*)(xo + (size_t)rr[k] * DM + col) = o;
;                 if (u) { const f32x4 m = o * s1 + h1; u32x2 w; w.x = cvt_pk_bf16(m[0], m[1]); w.y = cvt_pk_bf16(m[2], m[3]); *(u32x2*)(u + (size_t)rr[k] * DM + col) = w; } } }
.LBB0_1079:
	s_or_b64 exec, exec, s[0:1]
	ds_read_b128 v[52:55], v252 offset:3072
	ds_read_b128 v[56:59], v252 offset:11264
	ds_read_b128 v[60:63], v252 offset:19456
	v_mov_b32_e32 v24, v176
	v_mov_b32_e32 v25, v176
	s_mov_b64 s[0:1], 0xb828c00
	v_pk_mul_f32 v[48:49], v[196:197], v[24:25]
	v_pk_mul_f32 v[66:67], v[50:51], v[176:177]
	v_lshl_add_u64 v[64:65], v[172:173], 0, s[0:1]
	s_waitcnt lgkmcnt(0)
	v_pk_fma_f32 v[50:51], v[48:49], v[54:55], v[58:59]
	v_pk_add_f32 v[32:33], v[62:63], 1.0 op_sel_hi:[1,0]
	v_pk_add_f32 v[40:41], v[60:61], 1.0 op_sel_hi:[1,0]
	ds_read_b128 v[60:63], v252 offset:27648
	v_pk_fma_f32 v[48:49], v[66:67], v[52:53], v[56:57]
	s_waitcnt lgkmcnt(0)
	s_nop 0
	v_pk_fma_f32 v[50:51], v[50:51], v[32:33], v[62:63]
	v_pk_fma_f32 v[48:49], v[48:49], v[40:41], v[60:61]
	s_nop 0
	v_cvt_pk_bf16_f32 v48, v48, v49
	v_cvt_pk_bf16_f32 v49, v50, v51
	v_add_co_u32_e32 v50, vcc, 0xf828000, v184
	s_nop 1
	v_addc_co_u32_e32 v51, vcc, 0, v185, vcc
	global_store_dwordx2 v[50:51], v[48:49], off offset:1536
	s_and_saveexec_b64 s[0:1], s[4:5]
	s_cbranch_execz .LBB0_1081
	v_pk_mul_f32 v[44:45], v[44:45], v[0:1] op_sel_hi:[1,0]
	v_pk_mul_f32 v[48:49], v[46:47], v[0:1] op_sel_hi:[1,0]
	v_pk_fma_f32 v[46:47], v[44:45], v[54:55], v[58:59]
	v_pk_fma_f32 v[44:45], v[48:49], v[52:53], v[56:57]
	v_lshl_add_u64 v[48:49], v[138:139], 0, v[170:171]
	v_pk_fma_f32 v[32:33], v[46:47], v[32:33], v[62:63]
	v_pk_fma_f32 v[40:41], v[44:45], v[40:41], v[60:61]
	v_cvt_pk_bf16_f32 v40, v40, v41
	v_cvt_pk_bf16_f32 v41, v32, v33
	v_lshl_add_u64 v[32:33], v[152:153], 0, v[182:183]
	global_store_dwordx2 v[32:33], v[40:41], off
.LBB0_1081:
	s_or_b64 exec, exec, s[0:1]
	ds_read_b128 v[56:59], v252 offset:20480
	ds_read_b128 v[48:51], v252 offset:4096
	ds_read_b128 v[52:55], v252 offset:12288
	ds_read_b128 v[44:47], v252 offset:28672
	s_mov_b64 s[0:1], 0xb829000
	v_pk_mul_f32 v[40:41], v[194:195], v[24:25]
	v_pk_mul_f32 v[60:61], v[42:43], v[176:177]
	v_add_co_u32_e32 v62, vcc, 0xf828000, v184
	v_lshl_add_u64 v[64:65], v[172:173], 0, s[0:1]
	s_nop 0
	v_addc_co_u32_e32 v63, vcc, 0, v185, vcc
	s_waitcnt lgkmcnt(0)
	v_pk_add_f32 v[32:33], v[56:57], 1.0 op_sel_hi:[1,0]
	v_pk_add_f32 v[24:25], v[58:59], 1.0 op_sel_hi:[1,0]
	v_pk_fma_f32 v[42:43], v[40:41], v[50:51], v[54:55]
	v_pk_fma_f32 v[40:41], v[60:61], v[48:49], v[52:53]
	s_nop 1
	v_pk_fma_f32 v[40:41], v[40:41], v[32:33], v[44:45]
	v_pk_fma_f32 v[42:43], v[42:43], v[24:25], v[46:47]
	v_cvt_pk_bf16_f32 v40, v40, v41
	s_nop 0
	v_cvt_pk_bf16_f32 v41, v42, v43
	global_store_dwordx2 v[62:63], v[40:41], off offset:2048
	s_and_saveexec_b64 s[0:1], s[4:5]
	s_cbranch_execz .LBB0_1083
	v_pk_mul_f32 v[36:37], v[36:37], v[0:1] op_sel_hi:[1,0]
	v_pk_mul_f32 v[40:41], v[38:39], v[0:1] op_sel_hi:[1,0]
	v_pk_fma_f32 v[38:39], v[36:37], v[50:51], v[54:55]
	v_pk_fma_f32 v[36:37], v[40:41], v[48:49], v[52:53]
	v_lshl_add_u64 v[40:41], v[128:129], 0, v[170:171]
	v_pk_fma_f32 v[24:25], v[38:39], v[24:25], v[46:47]
	v_pk_fma_f32 v[32:33], v[36:37], v[32:33], v[44:45]
	v_cvt_pk_bf16_f32 v32, v32, v33
	v_cvt_pk_bf16_f32 v33, v24, v25
	v_lshl_add_u64 v[24:25], v[158:159], 0, v[182:183]
	global_store_dwordx2 v[24:25], v[32:33], off
.LBB0_1083:
	s_or_b64 exec, exec, s[0:1]
	ds_read_b128 v[36:39], v252 offset:5120
	ds_read_b128 v[40:43], v252 offset:13312
	ds_read_b128 v[44:47], v252 offset:21504
	v_mov_b32_e32 v24, v176
	v_mov_b32_e32 v25, v176
	s_mov_b64 s[0:1], 0xb829400
	v_pk_mul_f32 v[50:51], v[180:181], v[24:25]
	v_pk_mul_f32 v[34:35], v[34:35], v[176:177]
	v_lshl_add_u64 v[54:55], v[172:173], 0, s[0:1]
	s_waitcnt lgkmcnt(0)
	v_pk_fma_f32 v[52:53], v[50:51], v[38:39], v[42:43]
	v_pk_add_f32 v[32:33], v[46:47], 1.0 op_sel_hi:[1,0]
	v_pk_add_f32 v[48:49], v[44:45], 1.0 op_sel_hi:[1,0]
	ds_read_b128 v[44:47], v252 offset:29696
	v_pk_fma_f32 v[50:51], v[34:35], v[36:37], v[40:41]
	s_waitcnt lgkmcnt(0)
	v_pk_fma_f32 v[34:35], v[52:53], v[32:33], v[46:47]
	v_pk_fma_f32 v[50:51], v[50:51], v[48:49], v[44:45]
	s_nop 0
	v_cvt_pk_bf16_f32 v50, v50, v51
	v_cvt_pk_bf16_f32 v51, v34, v35
	v_add_co_u32_e32 v34, vcc, 0xf828000, v184
	s_nop 1
	v_addc_co_u32_e32 v35, vcc, 0, v185, vcc
	global_store_dwordx2 v[34:35], v[50:51], off offset:2560
	s_and_saveexec_b64 s[0:1], s[4:5]
	s_cbranch_execz .LBB0_1085
	v_pk_mul_f32 v[28:29], v[28:29], v[0:1] op_sel_hi:[1,0]
	v_pk_mul_f32 v[34:35], v[30:31], v[0:1] op_sel_hi:[1,0]
	v_pk_fma_f32 v[30:31], v[28:29], v[38:39], v[42:43]
	v_pk_fma_f32 v[28:29], v[34:35], v[36:37], v[40:41]
	v_lshl_add_u64 v[34:35], v[130:131], 0, v[170:171]
	s_nop 1
	v_pk_fma_f32 v[30:31], v[30:31], v[32:33], v[46:47]
	v_pk_fma_f32 v[28:29], v[28:29], v[48:49], v[44:45]
	s_nop 0
	v_cvt_pk_bf16_f32 v28, v28, v29
	v_cvt_pk_bf16_f32 v29, v30, v31
	v_lshl_add_u64 v[30:31], v[160:161], 0, v[182:183]
	global_store_dwordx2 v[30:31], v[28:29], off
; __device__ __forceinline__ unsigned cvt_pk_bf16(float lo, float hi) { unsigned r; asm volatile("v_cvt_pk_bf16_f32 %0, %1, %2" : "=v"(r) : "v"(lo), "v"(hi)); return r; }
; __device__ __forceinline__ void phase_ln(const float* z, float* xo, const float* __restrict__ g, const float* __restrict__ b, const float* __restrict__ sc, const float* __restrict__ sh, bf16_t* __restrict__ u) {
;     ...
;         for (int j = 0; j < 8; ++j) { const int col = j * 256 + 4 * lane;
;             const f32x4 gg = *(const f32x4*)(g + col), bb = *(const f32x4*)(b + col);
;             f32x4 s1 = {0.f, 0.f, 0.f, 0.f}, h1 = {0.f, 0.f, 0.f, 0.f};
;             if (u) { s1 = *(const f32x4*)(sc + col) + 1.0f; h1 = *(const f32x4*)(sh + col); }
; #pragma unroll
;             for (int k = 0; k < 2; ++k) { if (k == 1 && !hasB) continue;
;                 const f32x4 o = (v[k][j] - mean[k]) * rstd[k] * gg + bb;
;                 *(f32x4*)(xo + (size_t)rr[k] * DM + col) = o;
;                 if (u) { const f32x4 m = o * s1 + h1; u32x2 w; w.x = cvt_pk_bf16(m[0], m[1]); w.y = cvt_pk_bf16(m[2], m[3]); *(u32x2*)(u + (size_t)rr[k] * DM + col) = w; } } }
.LBB0_1085:
	s_or_b64 exec, exec, s[0:1]
	ds_read_b128 v[40:43], v252 offset:22528
	ds_read_b128 v[32:35], v252 offset:6144
	ds_read_b128 v[36:39], v252 offset:14336
	ds_read_b128 v[28:31], v252 offset:30720
	s_mov_b64 s[0:1], 0xb829800
	v_pk_mul_f32 v[44:45], v[178:179], v[24:25]
	v_pk_mul_f32 v[46:47], v[26:27], v[176:177]
	v_add_co_u32_e32 v48, vcc, 0xf828000, v184
	v_lshl_add_u64 v[50:51], v[172:173], 0, s[0:1]
	s_nop 0
	v_addc_co_u32_e32 v49, vcc, 0, v185, vcc
	s_waitcnt lgkmcnt(0)
	v_pk_add_f32 v[24:25], v[42:43], 1.0 op_sel_hi:[1,0]
	v_pk_add_f32 v[26:27], v[40:41], 1.0 op_sel_hi:[1,0]
	v_pk_fma_f32 v[42:43], v[44:45], v[34:35], v[38:39]
	v_pk_fma_f32 v[40:41], v[46:47], v[32:33], v[36:37]
	s_nop 1
	v_pk_fma_f32 v[40:41], v[40:41], v[26:27], v[28:29]
	v_pk_fma_f32 v[42:43], v[42:43], v[24:25], v[30:31]
	v_cvt_pk_bf16_f32 v40, v40, v41
	s_nop 0
	v_cvt_pk_bf16_f32 v41, v42, v43
	global_store_dwordx2 v[48:49], v[40:41], off offset:3072
	s_and_saveexec_b64 s[0:1], s[4:5]
	s_cbranch_execz .LBB0_1087
	v_pk_mul_f32 v[20:21], v[20:21], v[0:1] op_sel_hi:[1,0]
	v_pk_mul_f32 v[40:41], v[22:23], v[0:1] op_sel_hi:[1,0]
	v_pk_fma_f32 v[22:23], v[20:21], v[34:35], v[38:39]
	v_pk_fma_f32 v[20:21], v[40:41], v[32:33], v[36:37]
	v_lshl_add_u64 v[32:33], v[132:133], 0, v[170:171]
	s_nop 1
	v_pk_fma_f32 v[22:23], v[22:23], v[24:25], v[30:31]
	v_pk_fma_f32 v[20:21], v[20:21], v[26:27], v[28:29]
	s_nop 0
	v_cvt_pk_bf16_f32 v20, v20, v21
	v_cvt_pk_bf16_f32 v21, v22, v23
	v_lshl_add_u64 v[22:23], v[162:163], 0, v[182:183]
	global_store_dwordx2 v[22:23], v[20:21], off
.LBB0_1087:
	s_or_b64 exec, exec, s[0:1]
	ds_read_b128 v[32:35], v252 offset:23552
	ds_read_b128 v[24:27], v252 offset:7168
	ds_read_b128 v[28:31], v252 offset:15360
	ds_read_b128 v[20:23], v252 offset:31744
	v_mov_b32_e32 v36, v176
	v_mov_b32_e32 v37, v176
	s_mov_b64 s[0:1], 0xb829c00
	v_pk_mul_f32 v[40:41], v[18:19], v[176:177]
	v_pk_mul_f32 v[36:37], v[174:175], v[36:37]
	v_lshl_add_u64 v[38:39], v[172:173], 0, s[0:1]
	v_add_co_u32_e32 v42, vcc, 0xf828000, v184
	s_waitcnt lgkmcnt(0)
	v_pk_add_f32 v[18:19], v[34:35], 1.0 op_sel_hi:[1,0]
	v_pk_add_f32 v[32:33], v[32:33], 1.0 op_sel_hi:[1,0]
	v_pk_fma_f32 v[36:37], v[36:37], v[26:27], v[30:31]
	v_pk_fma_f32 v[34:35], v[40:41], v[24:25], v[28:29]
	v_addc_co_u32_e32 v43, vcc, 0, v185, vcc
	s_nop 0
	v_pk_fma_f32 v[34:35], v[34:35], v[32:33], v[20:21]
	v_pk_fma_f32 v[36:37], v[36:37], v[18:19], v[22:23]
	v_cvt_pk_bf16_f32 v34, v34, v35
	s_nop 0
	v_cvt_pk_bf16_f32 v35, v36, v37
	global_store_dwordx2 v[42:43], v[34:35], off offset:3584
	s_and_saveexec_b64 s[0:1], s[4:5]
	s_cbranch_execz .LBB0_1072
	v_pk_mul_f32 v[16:17], v[16:17], v[0:1] op_sel_hi:[1,0]
	v_pk_mul_f32 v[14:15], v[14:15], v[0:1] op_sel_hi:[1,0]
	v_pk_fma_f32 v[16:17], v[16:17], v[26:27], v[30:31]
	v_pk_fma_f32 v[14:15], v[14:15], v[24:25], v[28:29]
	v_lshl_add_u64 v[24:25], v[134:135], 0, v[170:171]
	s_nop 1
	v_pk_fma_f32 v[16:17], v[16:17], v[18:19], v[22:23]
	v_pk_fma_f32 v[14:15], v[14:15], v[32:33], v[20:21]
	s_nop 0
	v_cvt_pk_bf16_f32 v14, v14, v15
	v_cvt_pk_bf16_f32 v15, v16, v17
	v_lshl_add_u64 v[16:17], v[164:165], 0, v[182:183]
	global_store_dwordx2 v[16:17], v[14:15], off
	s_branch .LBB0_1072

; __device__ __forceinline__ unsigned cvt_pk_bf16(float lo, float hi) { unsigned r; asm volatile("v_cvt_pk_bf16_f32 %0, %1, %2" : "=v"(r) : "v"(lo), "v"(hi)); return r; }
; __device__ __forceinline__ void phase_ln(const float* z, float* xo, const float* __restrict__ g, const float* __restrict__ b, const float* __restrict__ sc, const float* __restrict__ sh, bf16_t* __restrict__ u) {
;     ...
;         for (int k = 0; k < 2; ++k) { mean[k] = wave_sum(s[k]) * (1.0f / DM); float q = 0.f;
; #pragma unroll
;             for (int j = 0; j < 8; ++j) { const f32x4 d = v[k][j] - mean[k]; q += (d[0] * d[0] + d[1] * d[1]) + (d[2] * d[2] + d[3] * d[3]); }
;             rstd[k] = 1.0f / sqrtf(wave_sum(q) * (1.0f / DM) + 1e-5f); }
; #pragma unroll
;         for (int j = 0; j < 8; ++j) { const int col = j * 256 + 4 * lane;
;             const f32x4 gg = *(const f32x4*)(g + col), bb = *(const f32x4*)(b + col);
;             f32x4 s1 = {0.f, 0.f, 0.f, 0.f}, h1 = {0.f, 0.f, 0.f, 0.f};
;             if (u) { s1 = *(const f32x4*)(sc + col) + 1.0f; h1 = *(const f32x4*)(sh + col); }
; #pragma unroll
;             for (int k = 0; k < 2; ++k) { if (k == 1 && !hasB) continue;
;                 const f32x4 o = (v[k][j] - mean[k]) * rstd[k] * gg + bb;
;                 *(f32x4*)(xo + (size_t)rr[k] * DM + col) = o;
;                 if (u) { const f32x4 m = o * s1 + h1; u32x2 w; w.x = cvt_pk_bf16(m[0], m[1]); w.y = cvt_pk_bf16(m[2], m[3]); *(u32x2*)(u + (size_t)rr[k] * DM + col) = w; } } }
.LBB0_1333:
	v_add_f32_e32 v12, v77, v156
	v_fmamk_f32 v12, v12, 0x3a000000, v220
	v_mul_f32_e32 v21, 0x4f800000, v12
	v_cmp_gt_f32_e32 vcc, s77, v12
	s_nop 1
	v_cndmask_b32_e32 v12, v12, v21, vcc
	v_sqrt_f32_e32 v21, v12
	s_nop 0
	v_add_u32_e32 v36, -1, v21
	v_fma_f32 v44, -v36, v21, v12
	v_add_u32_e32 v37, 1, v21
	v_cmp_ge_f32_e64 s[0:1], 0, v44
	s_nop 1
	v_cndmask_b32_e64 v36, v21, v36, s[0:1]
	v_fma_f32 v21, -v37, v21, v12
	v_cmp_lt_f32_e64 s[0:1], 0, v21
	s_nop 1
	v_cndmask_b32_e64 v21, v36, v37, s[0:1]
	v_mul_f32_e32 v36, 0x37800000, v21
	v_cndmask_b32_e32 v21, v21, v36, vcc
	v_cmp_class_f32_e32 vcc, v12, v219
	s_nop 1
	v_cndmask_b32_e32 v12, v21, v12, vcc
	v_div_scale_f32 v21, s[0:1], v12, v12, 1.0
	v_rcp_f32_e32 v36, v21
	s_nop 0
	v_fma_f32 v37, -v21, v36, 1.0
	v_fmac_f32_e32 v36, v37, v36
	v_div_scale_f32 v37, vcc, 1.0, v12, 1.0
	v_mul_f32_e32 v44, v37, v36
	v_fma_f32 v45, -v21, v44, v37
	v_fmac_f32_e32 v44, v45, v36
	v_fma_f32 v21, -v21, v44, v37
	v_div_fmas_f32 v21, v21, v36, v44
	v_div_fixup_f32 v12, v21, v12, 1.0
	v_pk_mul_f32 v[36:37], v[70:71], v[12:13] op_sel_hi:[1,0]
	v_pk_mul_f32 v[44:45], v[154:155], v[12:13] op_sel_hi:[1,0]
	v_pk_fma_f32 v[68:69], v[2:3], v[36:37], v[6:7]
	v_pk_fma_f32 v[70:71], v[4:5], v[44:45], v[8:9]
	v_lshl_add_u64 v[154:155], v[142:143], 0, v[0:1]
	s_and_b64 vcc, exec, s[6:7]
	global_store_dwordx4 v[154:155], v[68:71], off
	s_cbranch_vccnz .LBB0_1335
	s_waitcnt lgkmcnt(0)
	v_pk_fma_f32 v[44:45], v[68:69], v[164:165], v[72:73]
	v_pk_fma_f32 v[36:37], v[70:71], v[28:29], v[74:75]
	v_cvt_pk_bf16_f32 v44, v44, v45
	s_nop 0
	v_cvt_pk_bf16_f32 v45, v36, v37
	global_store_dwordx2 v[140:141], v[44:45], off
.LBB0_1335:
	v_add_f32_e32 v13, v13, v20
	v_fmamk_f32 v13, v13, 0x3a000000, v220
	v_mul_f32_e32 v20, 0x4f800000, v13
	v_cmp_gt_f32_e32 vcc, s77, v13
	s_nop 1
	v_cndmask_b32_e32 v13, v13, v20, vcc
	v_sqrt_f32_e32 v20, v13
	s_nop 0
	v_add_u32_e32 v21, -1, v20
	v_fma_f32 v37, -v21, v20, v13
	v_add_u32_e32 v36, 1, v20
	v_cmp_ge_f32_e64 s[0:1], 0, v37
	s_nop 1
	v_cndmask_b32_e64 v21, v20, v21, s[0:1]
	v_fma_f32 v20, -v36, v20, v13
	v_cmp_lt_f32_e64 s[0:1], 0, v20
	s_nop 1
	v_cndmask_b32_e64 v20, v21, v36, s[0:1]
	v_mul_f32_e32 v21, 0x37800000, v20
	v_cndmask_b32_e32 v20, v20, v21, vcc
	v_cmp_class_f32_e32 vcc, v13, v219
	s_nop 1
	v_cndmask_b32_e32 v13, v20, v13, vcc
	v_div_scale_f32 v20, s[0:1], v13, v13, 1.0
	v_rcp_f32_e32 v21, v20
	s_nop 0
	v_fma_f32 v36, -v20, v21, 1.0
	v_fmac_f32_e32 v21, v36, v21
	v_div_scale_f32 v36, vcc, 1.0, v13, 1.0
	v_mul_f32_e32 v37, v36, v21
	v_fma_f32 v44, -v20, v37, v36
	v_fmac_f32_e32 v37, v44, v21
	v_fma_f32 v20, -v20, v37, v36
	v_div_fmas_f32 v20, v20, v21, v37
	v_div_fixup_f32 v156, v20, v13, 1.0
	v_lshl_add_u64 v[20:21], v[88:89], 0, v[146:147]
	s_and_saveexec_b64 s[0:1], s[4:5]
	s_cbranch_execz .LBB0_1338
	v_pk_mul_f32 v[36:37], v[64:65], v[156:157] op_sel_hi:[1,0]
	v_pk_mul_f32 v[44:45], v[66:67], v[156:157] op_sel_hi:[1,0]
	v_pk_fma_f32 v[66:67], v[4:5], v[36:37], v[8:9]
	v_pk_fma_f32 v[64:65], v[2:3], v[44:45], v[6:7]
	s_and_b64 vcc, exec, s[6:7]
	global_store_dwordx4 v[20:21], v[64:67], off
	s_cbranch_vccnz .LBB0_1338
	s_waitcnt lgkmcnt(0)
	v_pk_fma_f32 v[28:29], v[66:67], v[28:29], v[74:75]
	v_pk_fma_f32 v[36:37], v[64:65], v[164:165], v[72:73]
	s_nop 0
	v_cvt_pk_bf16_f32 v36, v36, v37
	v_cvt_pk_bf16_f32 v37, v28, v29
	v_lshlrev_b64 v[28:29], 12, v[144:145]
	v_lshl_add_u64 v[28:29], v[90:91], 0, v[28:29]
	global_store_dwordx2 v[28:29], v[36:37], off

; __device__ __forceinline__ unsigned cvt_pk_bf16(float lo, float hi) { unsigned r; asm volatile("v_cvt_pk_bf16_f32 %0, %1, %2" : "=v"(r) : "v"(lo), "v"(hi)); return r; }
; __device__ __forceinline__ void phase_ln(const float* z, float* xo, const float* __restrict__ g, const float* __restrict__ b, const float* __restrict__ sc, const float* __restrict__ sh, bf16_t* __restrict__ u) {
;     ...
;         for (int j = 0; j < 8; ++j) { const int col = j * 256 + 4 * lane;
;             const f32x4 gg = *(const f32x4*)(g + col), bb = *(const f32x4*)(b + col);
;             f32x4 s1 = {0.f, 0.f, 0.f, 0.f}, h1 = {0.f, 0.f, 0.f, 0.f};
;             if (u) { s1 = *(const f32x4*)(sc + col) + 1.0f; h1 = *(const f32x4*)(sh + col); }
; #pragma unroll
;             for (int k = 0; k < 2; ++k) { if (k == 1 && !hasB) continue;
;                 const f32x4 o = (v[k][j] - mean[k]) * rstd[k] * gg + bb;
;                 *(f32x4*)(xo + (size_t)rr[k] * DM + col) = o;
;                 if (u) { const f32x4 m = o * s1 + h1; u32x2 w; w.x = cvt_pk_bf16(m[0], m[1]); w.y = cvt_pk_bf16(m[2], m[3]); *(u32x2*)(u + (size_t)rr[k] * DM + col) = w; } } }
.LBB0_1341:
	v_mov_b32_e32 v13, v12
	v_mov_b32_e32 v44, v12
	v_mov_b32_e32 v45, v12
	v_pk_mul_f32 v[44:45], v[168:169], v[44:45]
	v_pk_mul_f32 v[52:53], v[62:63], v[12:13]
	v_pk_fma_f32 v[62:63], v[44:45], v[66:67], v[70:71]
	v_pk_fma_f32 v[60:61], v[52:53], v[64:65], v[68:69]
	s_and_b64 vcc, exec, s[6:7]
	global_store_dwordx4 v[154:155], v[60:63], off offset:1024
	s_cbranch_vccnz .LBB0_1343
	s_waitcnt lgkmcnt(0)
	v_pk_fma_f32 v[52:53], v[60:61], v[28:29], v[72:73]
	v_pk_fma_f32 v[44:45], v[62:63], v[36:37], v[74:75]
	v_cvt_pk_bf16_f32 v52, v52, v53
	s_nop 0
	v_cvt_pk_bf16_f32 v53, v44, v45
	global_store_dwordx2 v[140:141], v[52:53], off offset:512
.LBB0_1343:
	s_and_saveexec_b64 s[0:1], s[4:5]
	s_cbranch_execz .LBB0_1346
	v_pk_mul_f32 v[44:45], v[56:57], v[156:157] op_sel_hi:[1,0]
	v_pk_mul_f32 v[52:53], v[58:59], v[156:157] op_sel_hi:[1,0]
	v_pk_fma_f32 v[58:59], v[44:45], v[66:67], v[70:71]
	v_pk_fma_f32 v[56:57], v[52:53], v[64:65], v[68:69]
	s_and_b64 vcc, exec, s[6:7]
	global_store_dwordx4 v[20:21], v[56:59], off offset:1024
	s_cbranch_vccnz .LBB0_1346
	s_waitcnt lgkmcnt(0)
	v_pk_fma_f32 v[36:37], v[58:59], v[36:37], v[74:75]
	v_pk_fma_f32 v[28:29], v[56:57], v[28:29], v[72:73]
	s_nop 0
	v_cvt_pk_bf16_f32 v28, v28, v29
	v_cvt_pk_bf16_f32 v29, v36, v37
	v_lshlrev_b64 v[36:37], 12, v[144:145]
	v_lshl_add_u64 v[36:37], v[90:91], 0, v[36:37]
	global_store_dwordx2 v[36:37], v[28:29], off offset:512

; __device__ __forceinline__ unsigned cvt_pk_bf16(float lo, float hi) { unsigned r; asm volatile("v_cvt_pk_bf16_f32 %0, %1, %2" : "=v"(r) : "v"(lo), "v"(hi)); return r; }
; __device__ __forceinline__ void phase_ln(const float* z, float* xo, const float* __restrict__ g, const float* __restrict__ b, const float* __restrict__ sc, const float* __restrict__ sh, bf16_t* __restrict__ u) {
;     ...
;         for (int j = 0; j < 8; ++j) { const int col = j * 256 + 4 * lane;
;             const f32x4 gg = *(const f32x4*)(g + col), bb = *(const f32x4*)(b + col);
;             f32x4 s1 = {0.f, 0.f, 0.f, 0.f}, h1 = {0.f, 0.f, 0.f, 0.f};
;             if (u) { s1 = *(const f32x4*)(sc + col) + 1.0f; h1 = *(const f32x4*)(sh + col); }
; #pragma unroll
;             for (int k = 0; k < 2; ++k) { if (k == 1 && !hasB) continue;
;                 const f32x4 o = (v[k][j] - mean[k]) * rstd[k] * gg + bb;
;                 *(f32x4*)(xo + (size_t)rr[k] * DM + col) = o;
;                 if (u) { const f32x4 m = o * s1 + h1; u32x2 w; w.x = cvt_pk_bf16(m[0], m[1]); w.y = cvt_pk_bf16(m[2], m[3]); *(u32x2*)(u + (size_t)rr[k] * DM + col) = w; } } }
.LBB0_1349:
	v_mov_b32_e32 v44, v12
	v_mov_b32_e32 v45, v12
	v_pk_mul_f32 v[44:45], v[166:167], v[44:45]
	v_pk_mul_f32 v[52:53], v[54:55], v[12:13]
	s_waitcnt lgkmcnt(0)
	v_pk_fma_f32 v[54:55], v[44:45], v[58:59], v[62:63]
	v_pk_fma_f32 v[52:53], v[52:53], v[56:57], v[60:61]
	s_and_b64 vcc, exec, s[6:7]
	global_store_dwordx4 v[154:155], v[52:55], off offset:2048
	s_cbranch_vccnz .LBB0_1351
	s_nop 0
	v_pk_fma_f32 v[52:53], v[52:53], v[28:29], v[64:65]
	v_pk_fma_f32 v[44:45], v[54:55], v[36:37], v[66:67]
	v_cvt_pk_bf16_f32 v52, v52, v53
	s_nop 0
	v_cvt_pk_bf16_f32 v53, v44, v45
	global_store_dwordx2 v[140:141], v[52:53], off offset:1024
.LBB0_1351:
	s_and_saveexec_b64 s[0:1], s[4:5]
	s_cbranch_execz .LBB0_1354
	v_pk_mul_f32 v[44:45], v[48:49], v[156:157] op_sel_hi:[1,0]
	v_pk_mul_f32 v[48:49], v[50:51], v[156:157] op_sel_hi:[1,0]
	v_pk_fma_f32 v[50:51], v[44:45], v[58:59], v[62:63]
	v_pk_fma_f32 v[48:49], v[48:49], v[56:57], v[60:61]
	s_and_b64 vcc, exec, s[6:7]
	global_store_dwordx4 v[20:21], v[48:51], off offset:2048
	s_cbranch_vccnz .LBB0_1354
	v_pk_fma_f32 v[36:37], v[50:51], v[36:37], v[66:67]
	v_pk_fma_f32 v[28:29], v[48:49], v[28:29], v[64:65]
	s_nop 0
	v_cvt_pk_bf16_f32 v28, v28, v29
	v_cvt_pk_bf16_f32 v29, v36, v37
	v_lshlrev_b64 v[36:37], 12, v[144:145]
	v_lshl_add_u64 v[36:37], v[90:91], 0, v[36:37]
	global_store_dwordx2 v[36:37], v[28:29], off offset:1024

; __device__ __forceinline__ unsigned cvt_pk_bf16(float lo, float hi) { unsigned r; asm volatile("v_cvt_pk_bf16_f32 %0, %1, %2" : "=v"(r) : "v"(lo), "v"(hi)); return r; }
; __device__ __forceinline__ void phase_ln(const float* z, float* xo, const float* __restrict__ g, const float* __restrict__ b, const float* __restrict__ sc, const float* __restrict__ sh, bf16_t* __restrict__ u) {
;     ...
;         for (int j = 0; j < 8; ++j) { const int col = j * 256 + 4 * lane;
;             const f32x4 gg = *(const f32x4*)(g + col), bb = *(const f32x4*)(b + col);
;             f32x4 s1 = {0.f, 0.f, 0.f, 0.f}, h1 = {0.f, 0.f, 0.f, 0.f};
;             if (u) { s1 = *(const f32x4*)(sc + col) + 1.0f; h1 = *(const f32x4*)(sh + col); }
; #pragma unroll
;             for (int k = 0; k < 2; ++k) { if (k == 1 && !hasB) continue;
;                 const f32x4 o = (v[k][j] - mean[k]) * rstd[k] * gg + bb;
;                 *(f32x4*)(xo + (size_t)rr[k] * DM + col) = o;
;                 if (u) { const f32x4 m = o * s1 + h1; u32x2 w; w.x = cvt_pk_bf16(m[0], m[1]); w.y = cvt_pk_bf16(m[2], m[3]); *(u32x2*)(u + (size_t)rr[k] * DM + col) = w; } } }
.LBB0_1357:
	v_mov_b32_e32 v44, v12
	v_mov_b32_e32 v45, v12
	v_pk_mul_f32 v[44:45], v[162:163], v[44:45]
	v_pk_mul_f32 v[60:61], v[46:47], v[12:13]
	s_waitcnt lgkmcnt(0)
	v_pk_fma_f32 v[46:47], v[44:45], v[50:51], v[54:55]
	v_pk_fma_f32 v[44:45], v[60:61], v[48:49], v[52:53]
	s_and_b64 vcc, exec, s[6:7]
	global_store_dwordx4 v[154:155], v[44:47], off offset:3072
	s_cbranch_vccnz .LBB0_1359
	s_nop 0
	v_pk_fma_f32 v[44:45], v[44:45], v[28:29], v[56:57]
	v_pk_fma_f32 v[46:47], v[46:47], v[36:37], v[58:59]
	v_cvt_pk_bf16_f32 v44, v44, v45
	s_nop 0
	v_cvt_pk_bf16_f32 v45, v46, v47
	global_store_dwordx2 v[140:141], v[44:45], off offset:1536
.LBB0_1359:
	s_and_saveexec_b64 s[0:1], s[4:5]
	s_cbranch_execz .LBB0_1362
	v_pk_mul_f32 v[40:41], v[40:41], v[156:157] op_sel_hi:[1,0]
	v_pk_mul_f32 v[44:45], v[42:43], v[156:157] op_sel_hi:[1,0]
	v_pk_fma_f32 v[42:43], v[40:41], v[50:51], v[54:55]
	v_pk_fma_f32 v[40:41], v[44:45], v[48:49], v[52:53]
	s_and_b64 vcc, exec, s[6:7]
	global_store_dwordx4 v[20:21], v[40:43], off offset:3072
	s_cbranch_vccnz .LBB0_1362
	v_pk_fma_f32 v[20:21], v[42:43], v[36:37], v[58:59]
	v_pk_fma_f32 v[28:29], v[40:41], v[28:29], v[56:57]
	s_nop 0
	v_cvt_pk_bf16_f32 v28, v28, v29
	v_cvt_pk_bf16_f32 v29, v20, v21
	v_lshlrev_b64 v[20:21], 12, v[144:145]
	v_lshl_add_u64 v[20:21], v[90:91], 0, v[20:21]
	global_store_dwordx2 v[20:21], v[28:29], off offset:1536

; __device__ __forceinline__ unsigned cvt_pk_bf16(float lo, float hi) { unsigned r; asm volatile("v_cvt_pk_bf16_f32 %0, %1, %2" : "=v"(r) : "v"(lo), "v"(hi)); return r; }
; __device__ __forceinline__ void phase_ln(const float* z, float* xo, const float* __restrict__ g, const float* __restrict__ b, const float* __restrict__ sc, const float* __restrict__ sh, bf16_t* __restrict__ u) {
;     ...
;         for (int j = 0; j < 8; ++j) { const int col = j * 256 + 4 * lane;
;             const f32x4 gg = *(const f32x4*)(g + col), bb = *(const f32x4*)(b + col);
;             f32x4 s1 = {0.f, 0.f, 0.f, 0.f}, h1 = {0.f, 0.f, 0.f, 0.f};
;             if (u) { s1 = *(const f32x4*)(sc + col) + 1.0f; h1 = *(const f32x4*)(sh + col); }
; #pragma unroll
;             for (int k = 0; k < 2; ++k) { if (k == 1 && !hasB) continue;
;                 const f32x4 o = (v[k][j] - mean[k]) * rstd[k] * gg + bb;
;                 *(f32x4*)(xo + (size_t)rr[k] * DM + col) = o;
;                 if (u) { const f32x4 m = o * s1 + h1; u32x2 w; w.x = cvt_pk_bf16(m[0], m[1]); w.y = cvt_pk_bf16(m[2], m[3]); *(u32x2*)(u + (size_t)rr[k] * DM + col) = w; } } }
.LBB0_1365:
	v_mov_b32_e32 v36, v12
	v_mov_b32_e32 v37, v12
	v_pk_mul_f32 v[36:37], v[160:161], v[36:37]
	v_pk_mul_f32 v[52:53], v[38:39], v[12:13]
	s_waitcnt lgkmcnt(0)
	v_pk_fma_f32 v[38:39], v[36:37], v[42:43], v[46:47]
	v_pk_fma_f32 v[36:37], v[52:53], v[40:41], v[44:45]
	v_add_co_u32_e32 v52, vcc, 0x1000, v154
	s_nop 1
	v_addc_co_u32_e32 v53, vcc, 0, v155, vcc
	s_and_b64 vcc, exec, s[6:7]
	global_store_dwordx4 v[52:53], v[36:39], off
	s_cbranch_vccnz .LBB0_1367
	s_nop 0
	v_pk_fma_f32 v[36:37], v[36:37], v[20:21], v[48:49]
	v_pk_fma_f32 v[38:39], v[38:39], v[28:29], v[50:51]
	v_cvt_pk_bf16_f32 v36, v36, v37
	s_nop 0
	v_cvt_pk_bf16_f32 v37, v38, v39
	global_store_dwordx2 v[140:141], v[36:37], off offset:2048
.LBB0_1367:
	s_and_saveexec_b64 s[0:1], s[4:5]
	s_cbranch_execz .LBB0_1370
	v_pk_mul_f32 v[32:33], v[32:33], v[156:157] op_sel_hi:[1,0]
	v_pk_mul_f32 v[36:37], v[34:35], v[156:157] op_sel_hi:[1,0]
	v_pk_fma_f32 v[34:35], v[32:33], v[42:43], v[46:47]
	v_pk_fma_f32 v[32:33], v[36:37], v[40:41], v[44:45]
	v_lshl_add_u64 v[36:37], v[106:107], 0, v[146:147]
	s_and_b64 vcc, exec, s[6:7]
	global_store_dwordx4 v[36:37], v[32:35], off
	s_cbranch_vccnz .LBB0_1370
	v_pk_fma_f32 v[28:29], v[34:35], v[28:29], v[50:51]
	v_pk_fma_f32 v[20:21], v[32:33], v[20:21], v[48:49]
	s_nop 0
	v_cvt_pk_bf16_f32 v20, v20, v21
	v_cvt_pk_bf16_f32 v21, v28, v29
	v_lshlrev_b64 v[28:29], 12, v[144:145]
	v_lshl_add_u64 v[28:29], v[90:91], 0, v[28:29]
	global_store_dwordx2 v[28:29], v[20:21], off offset:2048

; __device__ __forceinline__ unsigned cvt_pk_bf16(float lo, float hi) { unsigned r; asm volatile("v_cvt_pk_bf16_f32 %0, %1, %2" : "=v"(r) : "v"(lo), "v"(hi)); return r; }
; __device__ __forceinline__ void phase_ln(const float* z, float* xo, const float* __restrict__ g, const float* __restrict__ b, const float* __restrict__ sc, const float* __restrict__ sh, bf16_t* __restrict__ u) {
;     ...
;         for (int j = 0; j < 8; ++j) { const int col = j * 256 + 4 * lane;
;             const f32x4 gg = *(const f32x4*)(g + col), bb = *(const f32x4*)(b + col);
;             f32x4 s1 = {0.f, 0.f, 0.f, 0.f}, h1 = {0.f, 0.f, 0.f, 0.f};
;             if (u) { s1 = *(const f32x4*)(sc + col) + 1.0f; h1 = *(const f32x4*)(sh + col); }
; #pragma unroll
;             for (int k = 0; k < 2; ++k) { if (k == 1 && !hasB) continue;
;                 const f32x4 o = (v[k][j] - mean[k]) * rstd[k] * gg + bb;
;                 *(f32x4*)(xo + (size_t)rr[k] * DM + col) = o;
;                 if (u) { const f32x4 m = o * s1 + h1; u32x2 w; w.x = cvt_pk_bf16(m[0], m[1]); w.y = cvt_pk_bf16(m[2], m[3]); *(u32x2*)(u + (size_t)rr[k] * DM + col) = w; } } }
.LBB0_1373:
	v_mov_b32_e32 v28, v12
	v_mov_b32_e32 v29, v12
	v_pk_mul_f32 v[28:29], v[158:159], v[28:29]
	v_pk_mul_f32 v[46:47], v[30:31], v[12:13]
	s_waitcnt lgkmcnt(0)
	v_pk_fma_f32 v[30:31], v[28:29], v[34:35], v[38:39]
	v_pk_fma_f32 v[28:29], v[46:47], v[32:33], v[36:37]
	v_add_co_u32_e32 v46, vcc, 0x1000, v154
	s_nop 1
	v_addc_co_u32_e32 v47, vcc, 0, v155, vcc
	s_and_b64 vcc, exec, s[6:7]
	global_store_dwordx4 v[46:47], v[28:31], off offset:1024
	s_cbranch_vccnz .LBB0_1375
	s_nop 0
	v_pk_fma_f32 v[28:29], v[28:29], v[20:21], v[40:41]
	v_pk_fma_f32 v[30:31], v[30:31], v[44:45], v[42:43]
	v_cvt_pk_bf16_f32 v28, v28, v29
	s_nop 0
	v_cvt_pk_bf16_f32 v29, v30, v31
	global_store_dwordx2 v[140:141], v[28:29], off offset:2560
.LBB0_1375:
	s_and_saveexec_b64 s[0:1], s[4:5]
	s_cbranch_execz .LBB0_1378
	v_pk_mul_f32 v[24:25], v[24:25], v[156:157] op_sel_hi:[1,0]
	v_pk_mul_f32 v[28:29], v[26:27], v[156:157] op_sel_hi:[1,0]
	v_pk_fma_f32 v[26:27], v[24:25], v[34:35], v[38:39]
	v_pk_fma_f32 v[24:25], v[28:29], v[32:33], v[36:37]
	v_lshl_add_u64 v[28:29], v[116:117], 0, v[146:147]
	s_and_b64 vcc, exec, s[6:7]
	global_store_dwordx4 v[28:29], v[24:27], off
	s_cbranch_vccnz .LBB0_1378
	v_pk_fma_f32 v[20:21], v[24:25], v[20:21], v[40:41]
	v_lshlrev_b64 v[24:25], 12, v[144:145]
	v_lshl_add_u64 v[24:25], v[90:91], 0, v[24:25]
	v_pk_fma_f32 v[26:27], v[26:27], v[44:45], v[42:43]
	v_cvt_pk_bf16_f32 v20, v20, v21
	s_nop 0
	v_cvt_pk_bf16_f32 v21, v26, v27
	global_store_dwordx2 v[24:25], v[20:21], off offset:2560

; __device__ __forceinline__ unsigned cvt_pk_bf16(float lo, float hi) { unsigned r; asm volatile("v_cvt_pk_bf16_f32 %0, %1, %2" : "=v"(r) : "v"(lo), "v"(hi)); return r; }
; __device__ __forceinline__ void phase_ln(const float* z, float* xo, const float* __restrict__ g, const float* __restrict__ b, const float* __restrict__ sc, const float* __restrict__ sh, bf16_t* __restrict__ u) {
;     ...
;         for (int j = 0; j < 8; ++j) { const int col = j * 256 + 4 * lane;
;             const f32x4 gg = *(const f32x4*)(g + col), bb = *(const f32x4*)(b + col);
;             f32x4 s1 = {0.f, 0.f, 0.f, 0.f}, h1 = {0.f, 0.f, 0.f, 0.f};
;             if (u) { s1 = *(const f32x4*)(sc + col) + 1.0f; h1 = *(const f32x4*)(sh + col); }
; #pragma unroll
;             for (int k = 0; k < 2; ++k) { if (k == 1 && !hasB) continue;
;                 const f32x4 o = (v[k][j] - mean[k]) * rstd[k] * gg + bb;
;                 *(f32x4*)(xo + (size_t)rr[k] * DM + col) = o;
;                 if (u) { const f32x4 m = o * s1 + h1; u32x2 w; w.x = cvt_pk_bf16(m[0], m[1]); w.y = cvt_pk_bf16(m[2], m[3]); *(u32x2*)(u + (size_t)rr[k] * DM + col) = w; } } }
.LBB0_1381:
	v_mov_b32_e32 v20, v12
	v_mov_b32_e32 v21, v12
	v_pk_mul_f32 v[20:21], v[152:153], v[20:21]
	v_pk_mul_f32 v[40:41], v[22:23], v[12:13]
	s_waitcnt lgkmcnt(0)
	v_pk_fma_f32 v[22:23], v[20:21], v[26:27], v[30:31]
	v_pk_fma_f32 v[20:21], v[40:41], v[24:25], v[28:29]
	v_add_co_u32_e32 v40, vcc, 0x1000, v154
	s_nop 1
	v_addc_co_u32_e32 v41, vcc, 0, v155, vcc
	s_and_b64 vcc, exec, s[6:7]
	global_store_dwordx4 v[40:41], v[20:23], off offset:2048
	s_cbranch_vccnz .LBB0_1383
	s_nop 0
	v_pk_fma_f32 v[20:21], v[20:21], v[36:37], v[32:33]
	v_pk_fma_f32 v[22:23], v[22:23], v[38:39], v[34:35]
	v_cvt_pk_bf16_f32 v20, v20, v21
	s_nop 0
	v_cvt_pk_bf16_f32 v21, v22, v23
	global_store_dwordx2 v[140:141], v[20:21], off offset:3072
.LBB0_1383:
	s_and_saveexec_b64 s[0:1], s[4:5]
	s_cbranch_execz .LBB0_1386
	v_pk_mul_f32 v[16:17], v[16:17], v[156:157] op_sel_hi:[1,0]
	v_pk_mul_f32 v[20:21], v[18:19], v[156:157] op_sel_hi:[1,0]
	v_pk_fma_f32 v[18:19], v[16:17], v[26:27], v[30:31]
	v_pk_fma_f32 v[16:17], v[20:21], v[24:25], v[28:29]
	v_lshl_add_u64 v[20:21], v[126:127], 0, v[146:147]
	s_and_b64 vcc, exec, s[6:7]
	global_store_dwordx4 v[20:21], v[16:19], off
	s_cbranch_vccnz .LBB0_1386
	s_nop 0
	v_pk_fma_f32 v[18:19], v[18:19], v[38:39], v[34:35]
	v_pk_fma_f32 v[16:17], v[16:17], v[36:37], v[32:33]
	s_nop 0
	v_cvt_pk_bf16_f32 v16, v16, v17
	v_cvt_pk_bf16_f32 v17, v18, v19
	v_lshlrev_b64 v[18:19], 12, v[144:145]
	v_lshl_add_u64 v[18:19], v[90:91], 0, v[18:19]
	global_store_dwordx2 v[18:19], v[16:17], off offset:3072

; __device__ __forceinline__ unsigned cvt_pk_bf16(float lo, float hi) { unsigned r; asm volatile("v_cvt_pk_bf16_f32 %0, %1, %2" : "=v"(r) : "v"(lo), "v"(hi)); return r; }
; __device__ __forceinline__ void phase_ln(const float* z, float* xo, const float* __restrict__ g, const float* __restrict__ b, const float* __restrict__ sc, const float* __restrict__ sh, bf16_t* __restrict__ u) {
;     ...
;         for (int j = 0; j < 8; ++j) { const int col = j * 256 + 4 * lane;
;             const f32x4 gg = *(const f32x4*)(g + col), bb = *(const f32x4*)(b + col);
;             f32x4 s1 = {0.f, 0.f, 0.f, 0.f}, h1 = {0.f, 0.f, 0.f, 0.f};
;             if (u) { s1 = *(const f32x4*)(sc + col) + 1.0f; h1 = *(const f32x4*)(sh + col); }
; #pragma unroll
;             for (int k = 0; k < 2; ++k) { if (k == 1 && !hasB) continue;
;                 const f32x4 o = (v[k][j] - mean[k]) * rstd[k] * gg + bb;
;                 *(f32x4*)(xo + (size_t)rr[k] * DM + col) = o;
;                 if (u) { const f32x4 m = o * s1 + h1; u32x2 w; w.x = cvt_pk_bf16(m[0], m[1]); w.y = cvt_pk_bf16(m[2], m[3]); *(u32x2*)(u + (size_t)rr[k] * DM + col) = w; } } }
.LBB0_1389:
	v_mov_b32_e32 v32, v12
	v_mov_b32_e32 v33, v12
	v_pk_mul_f32 v[32:33], v[148:149], v[32:33]
	v_pk_mul_f32 v[12:13], v[14:15], v[12:13]
	s_waitcnt lgkmcnt(0)
	v_pk_fma_f32 v[14:15], v[32:33], v[18:19], v[22:23]
	v_add_co_u32_e32 v32, vcc, 0x1000, v154
	v_pk_fma_f32 v[12:13], v[12:13], v[16:17], v[20:21]
	s_nop 0
	v_addc_co_u32_e32 v33, vcc, 0, v155, vcc
	s_and_b64 vcc, exec, s[6:7]
	global_store_dwordx4 v[32:33], v[12:15], off offset:3072
	s_cbranch_vccnz .LBB0_1391
	s_nop 0
	v_pk_fma_f32 v[12:13], v[12:13], v[28:29], v[24:25]
	v_pk_fma_f32 v[14:15], v[14:15], v[30:31], v[26:27]
	v_cvt_pk_bf16_f32 v12, v12, v13
	s_nop 0
	v_cvt_pk_bf16_f32 v13, v14, v15
	global_store_dwordx2 v[140:141], v[12:13], off offset:3584
.LBB0_1391:
	s_and_saveexec_b64 s[0:1], s[4:5]
	s_cbranch_execz .LBB0_1330
	v_pk_mul_f32 v[12:13], v[150:151], v[156:157] op_sel_hi:[1,0]
	v_pk_mul_f32 v[10:11], v[10:11], v[156:157] op_sel_hi:[1,0]
	v_pk_fma_f32 v[12:13], v[12:13], v[18:19], v[22:23]
	v_pk_fma_f32 v[10:11], v[10:11], v[16:17], v[20:21]
	v_lshl_add_u64 v[14:15], v[136:137], 0, v[146:147]
	s_and_b64 vcc, exec, s[6:7]
	global_store_dwordx4 v[14:15], v[10:13], off
	s_cbranch_vccnz .LBB0_1330
	s_nop 0
	v_pk_fma_f32 v[12:13], v[12:13], v[30:31], v[26:27]
	v_pk_fma_f32 v[10:11], v[10:11], v[28:29], v[24:25]
	s_nop 0
	v_cvt_pk_bf16_f32 v10, v10, v11
	v_cvt_pk_bf16_f32 v11, v12, v13
	v_lshlrev_b64 v[12:13], 12, v[144:145]
	v_lshl_add_u64 v[12:13], v[90:91], 0, v[12:13]
	global_store_dwordx2 v[12:13], v[10:11], off offset:3584
	s_branch .LBB0_1330
